# XCC-local rounds that order against the neighbour batch: the neighbour's done flag is fetched together with the arrival atomic, the leader only polls if it was not yet set
# baseline (speedup 1.0000x reference)
; __device__ __forceinline__ unsigned xb_ld(unsigned* p)              { return __hip_atomic_load(p, __ATOMIC_RELAXED, __HIP_MEMORY_SCOPE_AGENT); }
; __device__ __forceinline__ unsigned xb_add(unsigned* p, unsigned v) { return __hip_atomic_fetch_add(p, v, __ATOMIC_RELAXED, __HIP_MEMORY_SCOPE_AGENT); }
; #define XB_SPIN(cond, bar) do { unsigned _sp = 0; while (cond) { __builtin_amdgcn_s_sleep(1); \
;     if ((++_sp & 255u) == 0u) { if (xb_ld(&(bar)[XB_TMO])) break; if (_sp > XB_SPIN_CAP) { atomicAdd(&(bar)[XB_TMO], 1u); break; } } } } while (0)
; __device__ __forceinline__ void xcd_barrier(const XcdBarrier& b, const int tid) {
;     ...
;         const unsigned old = xb_add(&bar[XB_XSUB(b.x)], 1u);
;         const unsigned gen = old / nloc;
;         if (old + 1u == (gen + 1u) * nloc) {
;             __builtin_amdgcn_fence(__ATOMIC_RELEASE, "agent");
;             asm volatile("s_waitcnt vmcnt(0)" ::: "memory");
;             const unsigned og = xb_add(&bar[XB_TOP], 1u);
;             const unsigned tg = og / nx;
;             if (og + 1u == (tg + 1u) * nx) xb_add(&bar[XB_TOPGEN], 1u);
;             else XB_SPIN(xb_ld(&bar[XB_TOPGEN]) == tg, bar);
;             __builtin_amdgcn_fence(__ATOMIC_ACQUIRE, "agent");
;             xb_add(&bar[XB_XGEN(b.x)], 1u);
;             asm volatile("s_waitcnt vmcnt(0)" ::: "memory");
;         } else {
;             XB_SPIN(xb_ld(&bar[XB_XGEN(b.x)]) == gen, bar);
.LBB0_586:
	s_mov_b64 s[4:5], exec
	v_mbcnt_lo_u32_b32 v0, s4, 0
	v_mbcnt_hi_u32_b32 v0, s5, v0
	v_cmp_eq_u32_e32 vcc, 0, v0
	s_and_saveexec_b64 s[2:3], vcc
	s_cbranch_execz .LBB0_588
	s_bcnt1_i32_b64 s4, s[4:5]
	v_mov_b32_e32 v4, s4
	v_readlane_b32 s4, v250, 9
	v_readlane_b32 s5, v250, 10
	s_nop 4
	global_atomic_add v4, v1, v4, s[4:5] sc0
	buffer_inv sc1
	s_cmp_eq_u32 s99, 1
	s_cbranch_scc0 .Lxb_nopf
	s_cmp_eq_u32 s48, 5
	s_cbranch_scc1 .Lxb_pf
	s_cmp_eq_u32 s48, 10
	s_cbranch_scc0 .Lxb_nopf
.Lxb_pf:
	v_readlane_b32 s5, v249, 0
	s_and_b32 s5, s5, 7
	s_cmp_eq_u32 s5, 0
	s_cbranch_scc1 .Lxb_nopf
	s_add_i32 s5, s5, -1
	s_lshl_b32 s5, s5, 2
	v_mov_b32_e32 v7, s5
	v_readlane_b32 s4, v252, 12
	v_readlane_b32 s5, v252, 13
	s_nop 4
	global_load_dword v7, v7, s[4:5] offset:2112 sc1
.Lxb_nopf:
.LBB0_588:
	s_or_b64 exec, exec, s[2:3]
	v_cvt_f32_u32_e32 v5, v3
	s_waitcnt vmcnt(0)
	v_readfirstlane_b32 s2, v4
	v_sub_u32_e32 v4, 0, v3
	v_rcp_iflag_f32_e32 v5, v5
	v_add_u32_e32 v6, s2, v0
	v_mul_f32_e32 v5, 0x4f7ffffe, v5
	v_cvt_u32_f32_e32 v5, v5
	v_mul_lo_u32 v0, v4, v5
	v_mul_hi_u32 v0, v5, v0
	v_add_u32_e32 v0, v5, v0
	v_mul_hi_u32 v0, v6, v0
	v_mul_lo_u32 v4, v0, v3
	v_sub_u32_e32 v4, v6, v4
	v_add_u32_e32 v5, 1, v0
	v_cmp_ge_u32_e32 vcc, v4, v3
	s_nop 1
	v_cndmask_b32_e32 v0, v0, v5, vcc
	v_sub_u32_e32 v5, v4, v3
	v_cndmask_b32_e32 v4, v4, v5, vcc
	v_add_u32_e32 v5, 1, v0
	v_cmp_ge_u32_e32 vcc, v4, v3
	v_add_u32_e32 v4, 1, v6
	s_nop 0
	v_cndmask_b32_e32 v0, v0, v5, vcc
	v_mul_lo_u32 v5, v3, v0
	v_add_u32_e32 v3, v5, v3
	v_cmp_ne_u32_e32 vcc, v4, v3
	v_readfirstlane_b32 s98, v0
	s_and_saveexec_b64 s[2:3], vcc
	s_xor_b64 s[2:3], exec, s[2:3]
	s_cbranch_execz .LBB0_602
	v_readlane_b32 s4, v250, 11
	v_readlane_b32 s5, v250, 12
	s_waitcnt lgkmcnt(0)
	s_nop 3
	global_load_dword v2, v1, s[4:5] sc1
	s_waitcnt vmcnt(0)
	v_cmp_eq_u32_e32 vcc, v2, v0
	s_and_saveexec_b64 s[4:5], vcc
	s_cbranch_execz .LBB0_601
	s_mov_b32 s20, 1
	s_mov_b64 s[6:7], 0
	s_branch .LBB0_592

; __device__ __forceinline__ unsigned xb_ld(unsigned* p)              { return __hip_atomic_load(p, __ATOMIC_RELAXED, __HIP_MEMORY_SCOPE_AGENT); }
; #define XB_SPIN(cond, bar) do { unsigned _sp = 0; while (cond) { __builtin_amdgcn_s_sleep(1); \
;     if ((++_sp & 255u) == 0u) { if (xb_ld(&(bar)[XB_TMO])) break; if (_sp > XB_SPIN_CAP) { atomicAdd(&(bar)[XB_TMO], 1u); break; } } } } while (0)
; __device__ __forceinline__ void xcd_barrier(const XcdBarrier& b, const int tid) {
;     ...
;             else XB_SPIN(xb_ld(&bar[XB_TOPGEN]) == tg, bar);
;             __builtin_amdgcn_fence(__ATOMIC_ACQUIRE, "agent");
.Lxb_wt:
	v_readlane_b32 s5, v249, 0
	s_and_b32 s5, s5, 7
	s_cmp_eq_u32 s5, 0
	s_cbranch_scc1 .Lxb_rel
	s_add_i32 s5, s5, -1
	s_lshl_b32 s5, s5, 2
	v_mov_b32_e32 v5, s5
	s_add_i32 s6, s48, -1
	s_mov_b32 s7, 0
	v_readlane_b32 s4, v252, 12
	v_readlane_b32 s5, v252, 13
	s_nop 4
	v_readfirstlane_b32 s8, v7
	s_cmp_ge_u32 s8, s6
	s_cbranch_scc1 .Lxb_rel
